# XCDs 4-7 run QKV(g+1) before attention(g), XCDs 0-3 the baseline order; snake MFMA order
# speedup vs baseline: 1.0059x; 1.0059x over previous
; __global__ void __launch_bounds__(NTHREADS, 2) fwd_megakernel(Args a) {
;     ...
;         switch (step) {
;             case 0: kind = 0; break;
;             case 1: kind = 1; p0 = 0; break;
;             case 2: kind = 2; p0 = 0; break;
;             case 3: kind = 3; break;
;             case 4: kind = 4; break;
;             case 5: kind = 2; p0 = 4; break;
;             case 6: kind = 1; p0 = 1; break;
;             case 7: kind = 2; p0 = 1; break;
;             case 8: kind = 1; p0 = 2; break;
;             case 9: kind = 2; p0 = 2; break;
;             case 10: kind = 5; p0 = 0; break;
;             case 11: kind = 6; p0 = 0; break;
;             case 12: kind = 5; p0 = 1; break;
;             case 13: kind = 6; p0 = 1; break;
;             case 14: kind = 5; p0 = 2; break;
;             case 15: kind = 6; p0 = 2; break;
;             case 16: kind = 2; p0 = 5; break;
;             case 17: kind = 1; p0 = 3; break;
;             default: kind = 2; p0 = 3; break;
;         }
.LBB0_14:
	v_readlane_b32 s0, v254, 21
	s_nop 1
	s_bitcmp1_b32 s0, 2
	s_cbranch_scc0 .Lsw_skip_a
	s_sub_i32 s0, s38, 11
	s_cmp_lt_u32 s0, 4
	s_cbranch_scc0 .Lsw_skip_a
	s_xor_b32 s0, s0, 1
	s_add_i32 s38, s0, 11

; __global__ void __launch_bounds__(NTHREADS, 2) fwd_megakernel(Args a) {
;     ...
;         switch (step) {
;             case 0: kind = 0; break;
;             case 1: kind = 1; p0 = 0; break;
;             case 2: kind = 2; p0 = 0; break;
;             case 3: kind = 3; break;
;             case 4: kind = 4; break;
;             case 5: kind = 2; p0 = 4; break;
;             case 6: kind = 1; p0 = 1; break;
;             case 7: kind = 2; p0 = 1; break;
;             case 8: kind = 1; p0 = 2; break;
;             case 9: kind = 2; p0 = 2; break;
;             case 10: kind = 5; p0 = 0; break;
;             case 11: kind = 6; p0 = 0; break;
;             case 12: kind = 5; p0 = 1; break;
;             case 13: kind = 6; p0 = 1; break;
;             case 14: kind = 5; p0 = 2; break;
;             case 15: kind = 6; p0 = 2; break;
;             case 16: kind = 2; p0 = 5; break;
;             case 17: kind = 1; p0 = 3; break;
;             default: kind = 2; p0 = 3; break;
;         }
.LBB0_552:
	v_readlane_b32 s0, v254, 21
	s_nop 1
	s_bitcmp1_b32 s0, 2
	s_cbranch_scc0 .Lsw_skip_b
	s_sub_i32 s0, s31, 11
	s_cmp_lt_u32 s0, 4
	s_cbranch_scc0 .Lsw_skip_b
	s_xor_b32 s0, s0, 1
	s_add_i32 s31, s0, 11

; __global__ void __launch_bounds__(NTHREADS, 2) fwd_megakernel(Args a) {
;     ...
;     for (int step = a.step_lo; step < a.step_hi; ++step) {
;     ...
;         if (step + 1 < a.step_hi && step != 11 && step != 13) { if (a.step_hi > 1000) cg::this_grid().sync(); else xcd_barrier(bar); }
;     }
.LBB0_567:
	s_or_b64 exec, exec, s[0:1]
	v_readlane_b32 s0, v254, 21
	s_nop 1
	s_bitcmp1_b32 s0, 2
	s_cbranch_scc0 .Lsw_skip_c
	s_sub_i32 s0, s31, 11
	s_cmp_lt_u32 s0, 4
	s_cbranch_scc0 .Lsw_skip_c
	s_xor_b32 s0, s0, 1
	s_add_i32 s31, s0, 11
